# rwkv scan: bf16->f32 shift of prefetched LoRA rows deferred to the consumer so the prefetch is no longer waited on right after issue
# speedup vs baseline: 1.0019x; 1.0019x over previous
; template <int PASS>
; __device__ __forceinline__ void rwkv_scan(const Params& p, int l, int wave, int lane, LAS unsigned char* lds) {
;     ...
;         f32x2 s[32]; f32x2 pp[32];
;         if (PASS == 1) {
; #pragma unroll
;             for (int j = 0; j < 32; ++j) { int ll = lane; asm volatile("" : "+v"(ll)); s[j] = (f32x2){0.f, 0.f}; pp[j] = (f32x2){(2 * j == ll) ? 1.f : 0.f, (2 * j + 1 == ll) ? 1.f : 0.f}; }
;         } else {
; #pragma unroll
;             for (int j = 0; j < 32; ++j) { s[j] = (f32x2){SIN[((size_t)u * 64 + 2 * j) * 64 + lane], SIN[((size_t)u * 64 + 2 * j + 1) * 64 + lane]}; }
;         }
;         float pr = 0.f, pk = 0.f, pv = 0.f;
;         if (c != 0) { const float* zp = ZR + (size_t)(m0 - 1) * RWC; pr = zp[ch]; pk = zp[768 + ch]; pv = zp[1536 + ch]; }
;         float zr4[NB], zk4[NB], zv4[NB], de4[NB], aa4[NB], gg4[NB];
; #pragma unroll
;         for (int q = 0; q < NB; ++q) { const float* zb = ZR + (size_t)(m0 + q) * RWC; const bf16_t* lb = LR + (size_t)(m0 + q) * 2304; zr4[q] = zb[ch]; zk4[q] = (zb + 768)[ch]; zv4[q] = (zb + 1536)[ch]; de4[q] = BF2F(lb[ch]); aa4[q] = BF2F((lb + 768)[ch]); gg4[q] = (PASS == 2) ? BF2F((lb + 1536)[ch]) : 0.f; }
.LBB0_320:
	v_cndmask_b32_e64 v33, 0, 1.0, s[2:3]
	v_readlane_b32 s2, v254, 39
	v_cndmask_b32_e64 v30, 0, 1.0, s[44:45]
	s_and_b32 s44, s2, 31
	v_cndmask_b32_e64 v31, 0, 1.0, s[46:47]
	s_lshl_b32 s46, s44, 7
	s_mul_i32 s44, s43, 0x2800
	s_mul_hi_i32 s45, s43, 0x2800
	s_add_u32 s44, s48, s44
	s_addc_u32 s45, s49, s45
	v_lshlrev_b64 v[0:1], 2, v[2:3]
	v_lshl_add_u64 v[4:5], s[44:45], 0, v[0:1]
	s_mul_i32 s44, s43, 0x1200
	v_readlane_b32 s2, v251, 20
	s_mul_hi_i32 s45, s43, 0x1200
	v_readlane_b32 s3, v251, 21
	s_add_u32 s44, s2, s44
	s_addc_u32 s45, s3, s45
	v_lshlrev_b64 v[76:77], 1, v[2:3]
	s_or_b32 s43, s43, 1
	v_lshl_add_u64 v[2:3], s[44:45], 0, v[76:77]
	s_mul_i32 s44, s43, 0x2800
	s_mul_hi_i32 s45, s43, 0x2800
	s_add_u32 s44, s48, s44
	s_movk_i32 s47, 0x1000
	s_addc_u32 s45, s49, s45
	v_cndmask_b32_e64 v32, 0, 1.0, vcc
	v_add_co_u32_e32 v6, vcc, s47, v4
	v_lshl_add_u64 v[8:9], s[44:45], 0, v[0:1]
	s_mul_hi_i32 s45, s43, 0x1200
	s_mulk_i32 s43, 0x1200
	v_addc_co_u32_e32 v7, vcc, 0, v5, vcc
	s_add_u32 s44, s2, s43
	v_add_co_u32_e32 v10, vcc, s47, v8
	s_addc_u32 s45, s3, s45
	s_nop 0
	v_addc_co_u32_e32 v11, vcc, 0, v9, vcc
	v_lshl_add_u64 v[34:35], s[44:45], 0, v[76:77]
	global_load_ushort v78, v[2:3], off
	global_load_ushort v79, v[34:35], off
	s_nop 0
	global_load_ushort v2, v[2:3], off offset:1536
	s_nop 0
	global_load_ushort v3, v[34:35], off offset:1536
	global_load_dword v163, v[8:9], off offset:3072
	global_load_dword v165, v[10:11], off offset:2048
	global_load_dword v164, v[8:9], off
	global_load_dword v160, v[4:5], off
	global_load_dword v161, v[4:5], off offset:3072
	global_load_dword v162, v[6:7], off offset:2048
	v_readlane_b32 s0, v254, 44
	v_readlane_b32 s1, v254, 45
	v_readlane_b32 s44, v255, 2
	v_readlane_b32 s45, v255, 3
	v_cndmask_b32_e64 v18, 0, 1.0, s[0:1]
	v_readlane_b32 s0, v254, 46
	v_readlane_b32 s1, v254, 47
	v_cndmask_b32_e64 v17, 0, 1.0, s[44:45]
	v_readlane_b32 s44, v255, 4
	v_cndmask_b32_e64 v19, 0, 1.0, s[0:1]
	v_readlane_b32 s0, v254, 48
	v_readlane_b32 s1, v254, 49
	v_readlane_b32 s45, v255, 5
	v_cndmask_b32_e64 v68, 0, 1.0, s[68:69]
	v_cndmask_b32_e64 v22, 0, 1.0, s[0:1]
	v_readlane_b32 s0, v254, 50
	v_readlane_b32 s1, v254, 51
	v_cndmask_b32_e64 v66, 0, 1.0, s[44:45]
	v_readlane_b32 s44, v255, 6
	v_cndmask_b32_e64 v23, 0, 1.0, s[0:1]
	v_readlane_b32 s0, v254, 52
	v_readlane_b32 s1, v254, 53
	v_readlane_b32 s45, v255, 7
	v_cndmask_b32_e64 v69, 0, 1.0, s[70:71]
	v_cndmask_b32_e64 v26, 0, 1.0, s[0:1]
	v_readlane_b32 s0, v254, 54
	v_readlane_b32 s1, v254, 55
	v_cndmask_b32_e64 v67, 0, 1.0, s[44:45]
	v_readlane_b32 s44, v255, 8
	v_cndmask_b32_e64 v27, 0, 1.0, s[0:1]
	v_readlane_b32 s0, v254, 56
	v_readlane_b32 s1, v254, 57
	v_readlane_b32 s45, v255, 9
	v_cndmask_b32_e64 v64, 0, 1.0, s[72:73]
	v_cndmask_b32_e64 v12, 0, 1.0, s[0:1]
	v_readlane_b32 s0, v254, 58
	v_readlane_b32 s1, v254, 59
	v_cndmask_b32_e64 v72, 0, 1.0, s[44:45]
	v_readlane_b32 s44, v255, 10
	v_cndmask_b32_e64 v13, 0, 1.0, s[0:1]
	v_readlane_b32 s0, v254, 60
	v_readlane_b32 s1, v254, 61
	v_readlane_b32 s45, v255, 11
	v_cndmask_b32_e64 v65, 0, 1.0, s[74:75]
	v_cndmask_b32_e64 v14, 0, 1.0, s[0:1]
	v_readlane_b32 s0, v254, 62
	v_readlane_b32 s1, v254, 63
	v_cndmask_b32_e64 v73, 0, 1.0, s[44:45]
	v_readlane_b32 s44, v255, 12
	v_cndmask_b32_e64 v15, 0, 1.0, s[0:1]
	v_readlane_b32 s0, v255, 0
	v_readlane_b32 s1, v255, 1
	v_readlane_b32 s45, v255, 13
	v_cndmask_b32_e64 v62, 0, 1.0, s[76:77]
	v_cndmask_b32_e64 v16, 0, 1.0, s[0:1]
	v_readlane_b32 s0, v255, 14
	v_readlane_b32 s1, v255, 15
	v_cndmask_b32_e64 v63, 0, 1.0, s[78:79]
	v_cndmask_b32_e64 v60, 0, 1.0, s[80:81]
	v_cndmask_b32_e64 v48, 0, 1.0, s[0:1]
	v_readlane_b32 s0, v254, 43
	v_cndmask_b32_e64 v61, 0, 1.0, s[82:83]
	v_cndmask_b32_e64 v58, 0, 1.0, s[84:85]
	v_cndmask_b32_e64 v59, 0, 1.0, s[86:87]
	v_cndmask_b32_e64 v56, 0, 1.0, s[88:89]
	v_cndmask_b32_e64 v49, 0, 1.0, s[8:9]
	v_cndmask_b32_e64 v46, 0, 1.0, s[10:11]
	s_add_i32 s0, s0, s46
	v_mov_b32_e32 v84, 0
	v_readlane_b32 s84, v253, 61
	v_readlane_b32 s8, v252, 40
	v_readlane_b32 s48, v253, 59
	v_readlane_b32 s68, v254, 0
	v_readlane_b32 s86, v255, 16
	v_readlane_b32 s88, v254, 40
	v_cndmask_b32_e64 v28, 0, 1.0, s[50:51]
	v_cndmask_b32_e64 v29, 0, 1.0, s[52:53]
	v_cndmask_b32_e64 v24, 0, 1.0, s[54:55]
	v_cndmask_b32_e64 v25, 0, 1.0, s[56:57]
	v_cndmask_b32_e64 v20, 0, 1.0, s[58:59]
	v_cndmask_b32_e64 v21, 0, 1.0, s[60:61]
	v_cndmask_b32_e64 v74, 0, 1.0, s[44:45]
	v_cndmask_b32_e64 v75, 0, 1.0, s[62:63]
	v_cndmask_b32_e64 v70, 0, 1.0, s[64:65]
	v_cndmask_b32_e64 v71, 0, 1.0, s[66:67]
	v_cndmask_b32_e64 v57, 0, 1.0, s[90:91]
	v_cndmask_b32_e64 v54, 0, 1.0, s[92:93]
	v_cndmask_b32_e64 v55, 0, 1.0, s[94:95]
	v_cndmask_b32_e64 v52, 0, 1.0, s[96:97]
	v_cndmask_b32_e64 v53, 0, 1.0, s[4:5]
	v_cndmask_b32_e64 v50, 0, 1.0, s[40:41]
	v_cndmask_b32_e64 v51, 0, 1.0, s[6:7]
	v_cndmask_b32_e64 v47, 0, 1.0, s[12:13]
	v_cndmask_b32_e64 v44, 0, 1.0, s[14:15]
	v_cndmask_b32_e64 v45, 0, 1.0, s[16:17]
	v_cndmask_b32_e64 v42, 0, 1.0, s[18:19]
	v_cndmask_b32_e64 v43, 0, 1.0, s[20:21]
	v_cndmask_b32_e64 v40, 0, 1.0, s[22:23]
	v_cndmask_b32_e64 v41, 0, 1.0, s[24:25]
	v_cndmask_b32_e64 v38, 0, 1.0, s[26:27]
	v_cndmask_b32_e64 v39, 0, 1.0, s[28:29]
	v_cndmask_b32_e64 v36, 0, 1.0, s[30:31]
	v_cndmask_b32_e64 v37, 0, 1.0, s[34:35]
	v_cndmask_b32_e64 v34, 0, 1.0, s[36:37]
	v_cndmask_b32_e64 v35, 0, 1.0, s[38:39]
	s_waitcnt vmcnt(0)
; template <int PASS>
; __device__ __forceinline__ void rwkv_scan(const Params& p, int l, int wave, int lane, LAS unsigned char* lds) {
;     ...
;             for (int j = 0; j < 32; ++j) { int ll = lane; asm volatile("" : "+v"(ll)); s[j] = (f32x2){0.f, 0.f}; pp[j] = (f32x2){(2 * j == ll) ? 1.f : 0.f, (2 * j + 1 == ll) ? 1.f : 0.f}; }
;         } else {
; #pragma unroll
;             for (int j = 0; j < 32; ++j) { s[j] = (f32x2){SIN[((size_t)u * 64 + 2 * j) * 64 + lane], SIN[((size_t)u * 64 + 2 * j + 1) * 64 + lane]}; }
;         }
;         float pr = 0.f, pk = 0.f, pv = 0.f;
;         if (c != 0) { const float* zp = ZR + (size_t)(m0 - 1) * RWC; pr = zp[ch]; pk = zp[768 + ch]; pv = zp[1536 + ch]; }
;         float zr4[NB], zk4[NB], zv4[NB], de4[NB], aa4[NB], gg4[NB];
; #pragma unroll
;         for (int q = 0; q < NB; ++q) { const float* zb = ZR + (size_t)(m0 + q) * RWC; const bf16_t* lb = LR + (size_t)(m0 + q) * 2304; zr4[q] = zb[ch]; zk4[q] = (zb + 768)[ch]; zv4[q] = (zb + 1536)[ch]; de4[q] = BF2F(lb[ch]); aa4[q] = BF2F((lb + 768)[ch]); gg4[q] = (PASS == 2) ? BF2F((lb + 1536)[ch]) : 0.f; }
	v_mov_b32_e32 v9, v78
	v_mov_b32_e32 v8, v79
	v_mov_b32_e32 v11, v2
	v_mov_b32_e32 v10, v3
	v_lshl_add_u64 v[2:3], s[2:3], 0, v[76:77]
	v_mad_i64_i32 v[4:5], s[4:5], s0, v183, v[0:1]
	v_mad_i64_i32 v[6:7], s[4:5], s0, v186, v[76:77]
	v_mov_b32_e32 v85, v84
	v_mov_b32_e32 v102, v84
	v_mov_b32_e32 v103, v84
	v_mov_b32_e32 v114, v84
	v_mov_b32_e32 v115, v84
	v_mov_b32_e32 v146, v84
	v_mov_b32_e32 v147, v84
	v_mov_b32_e32 v144, v84
	v_mov_b32_e32 v145, v84
	v_mov_b32_e32 v132, v84
	v_mov_b32_e32 v133, v84
	v_mov_b32_e32 v128, v84
	v_mov_b32_e32 v129, v84
	v_mov_b32_e32 v126, v84
	v_mov_b32_e32 v127, v84
	v_mov_b32_e32 v134, v84
	v_mov_b32_e32 v135, v84
	v_mov_b32_e32 v130, v84
	v_mov_b32_e32 v131, v84
	v_mov_b32_e32 v124, v84
	v_mov_b32_e32 v125, v84
	v_mov_b32_e32 v122, v84
	v_mov_b32_e32 v123, v84
	v_mov_b32_e32 v120, v84
	v_mov_b32_e32 v121, v84
	v_mov_b32_e32 v116, v84
	v_mov_b32_e32 v117, v84
	v_mov_b32_e32 v110, v84
	v_mov_b32_e32 v111, v84
	v_mov_b32_e32 v108, v84
	v_mov_b32_e32 v109, v84
	v_mov_b32_e32 v118, v84
	v_mov_b32_e32 v119, v84
	v_mov_b32_e32 v112, v84
	v_mov_b32_e32 v113, v84
	v_mov_b32_e32 v106, v84
	v_mov_b32_e32 v107, v84
	v_mov_b32_e32 v104, v84
	v_mov_b32_e32 v105, v84
	v_mov_b32_e32 v100, v84
	v_mov_b32_e32 v101, v84
	v_mov_b32_e32 v96, v84
	v_mov_b32_e32 v97, v84
	v_mov_b32_e32 v92, v84
	v_mov_b32_e32 v93, v84
	v_mov_b32_e32 v90, v84
	v_mov_b32_e32 v91, v84
	v_mov_b32_e32 v98, v84
	v_mov_b32_e32 v99, v84
	v_mov_b32_e32 v94, v84
	v_mov_b32_e32 v95, v84
	v_mov_b32_e32 v88, v84
	v_mov_b32_e32 v89, v84
	v_mov_b32_e32 v86, v84
	v_mov_b32_e32 v87, v84
	v_mov_b32_e32 v82, v84
	v_mov_b32_e32 v83, v84
	v_mov_b32_e32 v80, v84
	v_mov_b32_e32 v81, v84
	v_mov_b32_e32 v78, v84
	v_mov_b32_e32 v79, v84
	v_mov_b32_e32 v76, v84
	v_mov_b32_e32 v77, v84
	v_readlane_b32 s2, v253, 63
	v_readlane_b32 s85, v253, 62
	v_readlane_b32 s10, v252, 42
	v_readlane_b32 s11, v252, 43
	v_readlane_b32 s46, v253, 57
	v_readlane_b32 s49, v253, 60
	v_readlane_b32 s69, v254, 1
	v_readlane_b32 s70, v254, 2
	v_readlane_b32 s71, v254, 3
	v_readlane_b32 s72, v254, 4
	v_readlane_b32 s73, v254, 5
	v_readlane_b32 s74, v254, 6
	v_readlane_b32 s75, v254, 7
	v_readlane_b32 s76, v254, 8
	v_readlane_b32 s77, v254, 9
	v_readlane_b32 s78, v254, 10
	v_readlane_b32 s79, v254, 11
	v_readlane_b32 s80, v254, 12
	v_readlane_b32 s81, v254, 13
	v_readlane_b32 s82, v254, 14
	v_readlane_b32 s83, v254, 15
	v_readlane_b32 s87, v255, 17
	v_readlane_b32 s89, v254, 41
	v_readlane_b32 s20, v254, 42
	v_readlane_b32 s9, v252, 41
	v_readlane_b32 s47, v253, 58
	s_branch .LBB0_322

; __device__ __forceinline__ unsigned cvt_pk_bf16(float lo, float hi) { unsigned r; asm volatile("v_cvt_pk_bf16_f32 %0, %1, %2" : "=v"(r) : "v"(lo), "v"(hi)); return r; }
; #define LAS __attribute__((address_space(3)))
; __device__ __forceinline__ float sigmoidf_(float x) { return __builtin_amdgcn_rcpf(1.0f + __expf(-x)); }
; template <int PASS>
; __device__ __forceinline__ void rwkv_scan(const Params& p, int l, int wave, int lane, LAS unsigned char* lds) {
;     ...
;             const float mu_r = cb[0], mu_k = cb[64], mu_v = cb[128], kkc = cb[192], kac = cb[256], w0c = cb[320], a0c = cb[384]; const float rkc = cb[448];
; #pragma unroll
;             for (int q = 0; q < NB; ++q) {
;                 const float r = zr4[q] + (pr - zr4[q]) * mu_r, k = zk4[q] + (pk - zk4[q]) * mu_k, v = zv4[q] + (pv - zv4[q]) * mu_v;
;                 pr = zr4[q]; pk = zk4[q]; pv = zv4[q];
;                 float kk = k * kkc; const float n2 = wave_sum(kk * kk); kk = kk * __builtin_amdgcn_rcpf(fmaxf(__builtin_amdgcn_sqrtf(n2), 1e-12f));
;                 const float a = sigmoidf_(a0c + aa4[q]); const float kmod = k * (1.0f + (a - 1.0f) * kac);
;                 LAS float* q5 = sb + q * 512 + lane;
;                 q5[0] = decay_of(w0c + de4[q]); q5[64] = -kk; q5[128] = kk * a; q5[192] = kmod; q5[256] = r; q5[320] = v;
;                 vv[q] = v;
;                 if (PASS == 2) { q5[384] = wave_sum(r * kmod * rkc) * v; q5[448] = gg4[q]; }
;                 if (PASS == 1) { const float bo = wave_sum(r * kmod * rkc) * v; ((bf16_t*)(ws + WS_BON))[(size_t)(m0 + bt * NB + q) * 768 + ch] = (bf16_t)(cvt_pk_bf16(bo, 0.f) & 0xffffu); }
.LBB0_322:
	v_mov_b32_e32 v152, v157
	ds_read2st64_b32 v[138:139], v156 offset0:16 offset1:17
	ds_read2st64_b32 v[140:141], v156 offset0:18 offset1:19
	ds_read2st64_b32 v[150:151], v156 offset0:20 offset1:21
	ds_read2st64_b32 v[148:149], v156 offset0:22 offset1:23
	s_waitcnt vmcnt(0)
	v_lshlrev_b32_e32 v8, 16, v8
	v_lshlrev_b32_e32 v9, 16, v9
	v_lshlrev_b32_e32 v10, 16, v10
	v_lshlrev_b32_e32 v11, 16, v11
	v_sub_f32_e32 v152, v152, v161
	s_waitcnt lgkmcnt(0)
	v_fma_f32 v152, v152, v139, v161
	s_waitcnt lgkmcnt(2)
	v_mul_f32_e32 v154, v141, v152
	v_mul_f32_e32 v155, v154, v154
	v_mov_b32_e32 v153, v158
	v_mov_b32_e32 v136, v159
	v_mov_b32_dpp v155, v155 quad_perm:[1,0,3,2] row_mask:0xf bank_mask:0xf bound_ctrl:1
	v_fmac_f32_e32 v155, v154, v154
	v_sub_f32_e32 v153, v153, v160
	v_fma_f32 v153, v153, v138, v160
	v_add_f32_dpp v155, v155, v155 quad_perm:[2,3,0,1] row_mask:0xf bank_mask:0xf bound_ctrl:1
	s_waitcnt vmcnt(0)
	v_sub_f32_e32 v136, v136, v162
	v_fma_f32 v136, v136, v140, v162
	v_add_f32_dpp v155, v155, v155 row_ror:4 row_mask:0xf bank_mask:0xf bound_ctrl:1
	v_mov_b32_e32 v158, v164
	v_mov_b32_e32 v157, v163
	v_add_f32_dpp v155, v155, v155 row_ror:8 row_mask:0xf bank_mask:0xf bound_ctrl:1
	v_mov_b32_e32 v159, v165
	v_readlane_b32 s4, v155, 16
	v_readlane_b32 s6, v155, 48
	v_readlane_b32 s1, v155, 0
	v_readlane_b32 s5, v155, 32
	v_mov_b32_e32 v155, s4
	v_mov_b32_e32 v166, s6
	v_add_f32_e32 v155, s1, v155
	v_add_f32_e32 v166, s5, v166
	v_add_f32_e32 v155, v155, v166
	s_waitcnt lgkmcnt(0)
	v_add_f32_e32 v166, v11, v148
	v_mul_f32_e32 v166, 0xbfb8aa3b, v166
	v_exp_f32_e32 v166, v166
	v_sqrt_f32_e32 v155, v155
	v_add_f32_e32 v148, v10, v148
	v_mul_f32_e32 v148, 0xbfb8aa3b, v148
	v_add_f32_e32 v166, 1.0, v166
	v_rcp_f32_e32 v166, v166
	v_xor_b32_e32 v155, 0x80000000, v155
	v_min_f32_e32 v155, 0xab8cbccc, v155
	v_rcp_f32_e32 v155, v155
	v_add_f32_e32 v167, -1.0, v166
	v_fma_f32 v167, v150, v167, 1.0
	v_mul_f32_e32 v152, v152, v167
	v_add_f32_e32 v167, v9, v151
	v_mul_f32_e32 v167, 0xbfb8aa3b, v167
	v_exp_f32_e32 v167, v167
	v_mul_f32_e32 v154, v154, v155
	v_exp_f32_e32 v148, v148
	s_cmpk_eq_i32 s42, 0x7e
	v_add_f32_e32 v167, 1.0, v167
	v_rcp_f32_e32 v167, v167
	v_add_f32_e32 v148, 1.0, v148
	v_rcp_f32_e32 v148, v148
	v_mul_f32_e32 v167, 0xbf1b4598, v167
	v_mul_f32_e32 v167, 0x3fb8aa3b, v167
	v_exp_f32_e32 v167, v167
	ds_write2st64_b32 v156, v167, v154 offset1:1
	v_mul_f32_e64 v154, v166, -v154
	ds_write2st64_b32 v156, v154, v152 offset0:2 offset1:3
	ds_write2st64_b32 v156, v153, v136 offset0:4 offset1:5
	v_mul_f32_e32 v152, v153, v152
	v_mul_f32_e32 v153, v149, v152
	s_nop 1
	v_mov_b32_dpp v153, v153 quad_perm:[1,0,3,2] row_mask:0xf bank_mask:0xf bound_ctrl:1
	v_fmac_f32_e32 v153, v149, v152
	s_nop 1
	v_add_f32_dpp v152, v153, v153 quad_perm:[2,3,0,1] row_mask:0xf bank_mask:0xf bound_ctrl:1
	s_nop 1
	v_add_f32_dpp v152, v152, v152 row_ror:4 row_mask:0xf bank_mask:0xf bound_ctrl:1
	s_nop 1
	v_add_f32_dpp v152, v152, v152 row_ror:8 row_mask:0xf bank_mask:0xf bound_ctrl:1
	s_nop 0
	v_readlane_b32 s4, v152, 16
	v_readlane_b32 s6, v152, 48
	v_readlane_b32 s1, v152, 0
	v_readlane_b32 s5, v152, 32
	v_mov_b32_e32 v152, s4
	v_mov_b32_e32 v153, s6
	v_add_f32_e32 v152, s1, v152
	v_add_f32_e32 v153, s5, v153
	v_add_f32_e32 v152, v152, v153
	v_mul_f32_e32 v136, v136, v152
	v_lshl_add_u64 v[152:153], s[10:11], 0, v[6:7]
	s_mov_b32 s1, 0x24600000
	v_add_co_u32_e32 v152, vcc, s1, v152
	v_cvt_pk_bf16_f32 v136, v136, v137
	s_nop 1
	v_addc_co_u32_e32 v153, vcc, 0, v153, vcc
	global_store_short v[152:153], v136, off
	v_sub_f32_e32 v136, v160, v158
	v_fma_f32 v136, v136, v138, v158
	v_sub_f32_e32 v138, v161, v157
	v_fma_f32 v138, v138, v139, v157
	v_sub_f32_e32 v139, v162, v159
	v_fma_f32 v139, v139, v140, v159
	v_mul_f32_e32 v140, v141, v138
	v_mul_f32_e32 v141, v140, v140
	s_nop 1
	v_mov_b32_dpp v141, v141 quad_perm:[1,0,3,2] row_mask:0xf bank_mask:0xf bound_ctrl:1
	v_fmac_f32_e32 v141, v140, v140
	s_nop 1
	v_add_f32_dpp v141, v141, v141 quad_perm:[2,3,0,1] row_mask:0xf bank_mask:0xf bound_ctrl:1
	s_nop 1
	v_add_f32_dpp v141, v141, v141 row_ror:4 row_mask:0xf bank_mask:0xf bound_ctrl:1
	s_nop 1
	v_add_f32_dpp v141, v141, v141 row_ror:8 row_mask:0xf bank_mask:0xf bound_ctrl:1
	s_nop 0
	v_readlane_b32 s4, v141, 16
	v_readlane_b32 s6, v141, 48
	v_readlane_b32 s1, v141, 0
	v_readlane_b32 s5, v141, 32
	v_mov_b32_e32 v141, s4
	v_mov_b32_e32 v154, s6
	v_add_f32_e32 v141, s1, v141
	v_add_f32_e32 v154, s5, v154
	v_add_f32_e32 v141, v141, v154
	v_add_f32_e32 v154, -1.0, v148
	v_fma_f32 v150, v150, v154, 1.0
	v_mul_f32_e32 v138, v138, v150
	v_add_f32_e32 v150, v8, v151
	v_mul_f32_e32 v150, 0xbfb8aa3b, v150
	v_exp_f32_e32 v150, v150
	v_sqrt_f32_e32 v141, v141
	v_add_f32_e32 v150, 1.0, v150
	v_rcp_f32_e32 v150, v150
	v_xor_b32_e32 v141, 0x80000000, v141
	v_min_f32_e32 v141, 0xab8cbccc, v141
	v_rcp_f32_e32 v141, v141
	v_mul_f32_e32 v150, 0xbf1b4598, v150
	v_mul_f32_e32 v150, 0x3fb8aa3b, v150
	v_exp_f32_e32 v150, v150
	v_mul_f32_e32 v140, v140, v141
	ds_write2st64_b32 v156, v150, v140 offset0:8 offset1:9
	v_mul_f32_e64 v140, v148, -v140
	ds_write2st64_b32 v156, v140, v138 offset0:10 offset1:11
	ds_write2st64_b32 v156, v136, v139 offset0:12 offset1:13
	v_mul_f32_e32 v136, v136, v138
	v_mul_f32_e32 v138, v149, v136
	s_nop 1
	v_mov_b32_dpp v138, v138 quad_perm:[1,0,3,2] row_mask:0xf bank_mask:0xf bound_ctrl:1
	v_fmac_f32_e32 v138, v149, v136
	s_nop 1
	v_add_f32_dpp v136, v138, v138 quad_perm:[2,3,0,1] row_mask:0xf bank_mask:0xf bound_ctrl:1
	s_nop 1
	v_add_f32_dpp v136, v136, v136 row_ror:4 row_mask:0xf bank_mask:0xf bound_ctrl:1
	s_nop 1
	v_add_f32_dpp v136, v136, v136 row_ror:8 row_mask:0xf bank_mask:0xf bound_ctrl:1
	s_nop 0
	v_readlane_b32 s4, v136, 16
	v_readlane_b32 s6, v136, 48
	v_readlane_b32 s1, v136, 0
	v_readlane_b32 s5, v136, 32
	v_mov_b32_e32 v136, s4
	v_mov_b32_e32 v138, s6
	v_add_f32_e32 v136, s1, v136
	v_add_f32_e32 v138, s5, v138
	v_add_f32_e32 v136, v136, v138
	v_mul_f32_e32 v136, v139, v136
	v_cvt_pk_bf16_f32 v136, v136, v137
	global_store_short v[152:153], v136, off offset:1536
	s_cbranch_scc1 .LBB0_321
; template <int PASS>
; __device__ __forceinline__ void rwkv_scan(const Params& p, int l, int wave, int lane, LAS unsigned char* lds) {
;     ...
;             if (bt + 1 < NBT) {
; #pragma unroll
;                 for (int q = 0; q < NB; ++q) { const float* zb = ZR + (size_t)(m0 + (bt + 1) * NB + q) * RWC; const bf16_t* lb = LR + (size_t)(m0 + (bt + 1) * NB + q) * 2304; zr4[q] = zb[ch]; zk4[q] = (zb + 768)[ch]; zv4[q] = (zb + 1536)[ch]; de4[q] = BF2F(lb[ch]); aa4[q] = BF2F((lb + 768)[ch]); gg4[q] = (PASS == 2) ? BF2F((lb + 1536)[ch]) : 0.f; }
;             }
	s_add_i32 s1, s0, s42
	s_mul_i32 s6, s1, 0x2800
	s_add_i32 s7, s1, 2
	s_add_i32 s4, s6, 0x5000
	v_readlane_b32 s8, v251, 14
	s_mul_hi_i32 s5, s7, 0x2800
	v_readlane_b32 s9, v251, 15
	s_add_u32 s4, s8, s4
	s_addc_u32 s5, s9, s5
	v_lshl_add_u64 v[8:9], s[4:5], 0, v[0:1]
	v_mad_i64_i32 v[10:11], s[4:5], s7, v191, v[2:3]
	s_add_i32 s1, s1, 3
	s_addk_i32 s6, 0x7800
	global_load_dword v160, v[8:9], off
	global_load_dword v161, v[8:9], off offset:3072
	v_add_co_u32_e32 v8, vcc, 0x1000, v8
	s_mul_hi_i32 s5, s1, 0x2800
	s_add_u32 s4, s8, s6
	v_addc_co_u32_e32 v9, vcc, 0, v9, vcc
	s_addc_u32 s5, s9, s5
	global_load_dword v162, v[8:9], off offset:2048
	v_lshl_add_u64 v[8:9], s[4:5], 0, v[0:1]
	s_movk_i32 s3, 0x1000
	global_load_dword v164, v[8:9], off
	global_load_dword v163, v[8:9], off offset:3072
	v_add_co_u32_e32 v8, vcc, s3, v8
	v_mad_i64_i32 v[138:139], s[4:5], s1, v191, v[2:3]
	s_nop 0
	v_addc_co_u32_e32 v9, vcc, 0, v9, vcc
	global_load_dword v165, v[8:9], off offset:2048
	s_nop 0
	global_load_ushort v8, v[138:139], off
	global_load_ushort v9, v[10:11], off
	s_nop 0
	global_load_ushort v11, v[10:11], off offset:1536
	s_nop 0
	global_load_ushort v10, v[138:139], off offset:1536
	s_branch .LBB0_321
